# NA attention: 32 serialized exec-masked rel-pos-bias LDS loads per tile replaced by batched loads + v_cndmask with the same lane masks
# speedup vs baseline: 1.0205x; 1.0091x over previous
; template <int KW, int DV, bool NA> ...
;     ...
;         if (NA && i < n1) {
;             const int kr = na_row0 + i, dr = kr - na_r + 7;
;             const int cs = min(max(na_c - 8, 0), 48);
;             const float* rb = rpbs + dr * 31 - na_c + 15;
; #pragma unroll
;             for (int r = 0; r < 16; ++r) {
;                 const int kc0 = (r & 3) + 8 * (r >> 2) + 4 * hi, kc1 = kc0 + 32;
;                 const bool ok0 = (kc0 >= cs) && (kc0 < cs + 16), ok1 = (kc1 >= cs) && (kc1 < cs + 16);
;                 p0[r] = ok0 ? p0[r] + rb[kc0] : -1e30f;
;                 p1[r] = ok1 ? p1[r] + rb[kc1] : -1e30f;
;             }
;         }
.LBB0_430:
	s_or_b64 exec, exec, s[74:75]
	s_add_i32 s7, s2, -4
	v_cmp_ge_i32_e64 s[82:83], s7, v163
	v_cmp_lt_i32_e64 s[74:75], s7, v163
	s_and_saveexec_b64 s[26:27], s[74:75]
	v_cmp_ge_i32_e64 s[0:1], s7, v164
	v_cmp_lt_i32_e64 s[78:79], s7, v165
	s_and_b64 s[0:1], s[0:1], s[78:79]
	s_andn2_b64 s[78:79], s[82:83], exec
	s_and_b64 s[0:1], s[0:1], exec
	s_or_b64 s[82:83], s[78:79], s[0:1]
	s_or_b64 exec, exec, s[26:27]
	s_and_saveexec_b64 s[78:79], s[82:83]
	s_cbranch_execz .LBB0_504
	s_movk_i32 s0, 0x5400
	v_mul_lo_u32 v0, v174, s0
	v_add_u32_e32 v0, 0, v0
	v_add3_u32 v86, v0, v166, v167
	ds_read_b128 v[50:53], v86
	ds_read_b128 v[82:85], v86 offset:4608
	s_waitcnt lgkmcnt(1)
	v_mfma_f32_32x32x16_bf16 v[66:81], v[50:53], v[114:117], v[34:49]
	s_waitcnt lgkmcnt(0)
	v_mfma_f32_32x32x16_bf16 v[50:65], v[82:85], v[114:117], v[34:49]
	ds_read_b128 v[82:85], v86 offset:32
	s_waitcnt lgkmcnt(0)
	v_mfma_f32_32x32x16_bf16 v[66:81], v[82:85], v[118:121], v[66:81]
	ds_read_b128 v[82:85], v86 offset:4640
	s_waitcnt lgkmcnt(0)
	v_mfma_f32_32x32x16_bf16 v[50:65], v[82:85], v[118:121], v[50:65]
	ds_read_b128 v[82:85], v86 offset:64
	s_waitcnt lgkmcnt(0)
	v_mfma_f32_32x32x16_bf16 v[66:81], v[82:85], v[122:125], v[66:81]
	ds_read_b128 v[82:85], v86 offset:4672
	s_waitcnt lgkmcnt(0)
	v_mfma_f32_32x32x16_bf16 v[50:65], v[82:85], v[122:125], v[50:65]
	ds_read_b128 v[82:85], v86 offset:96
	s_waitcnt lgkmcnt(0)
	v_mfma_f32_32x32x16_bf16 v[66:81], v[82:85], v[126:129], v[66:81]
	ds_read_b128 v[82:85], v86 offset:4704
	s_waitcnt lgkmcnt(0)
	v_mfma_f32_32x32x16_bf16 v[50:65], v[82:85], v[126:129], v[50:65]
	s_and_saveexec_b64 s[0:1], s[74:75]
	s_cbranch_execz .LBB0_499
	ds_read_b32 v98, v172
	ds_read_b32 v82, v172 offset:128
	ds_read_b32 v99, v172 offset:4
	ds_read_b32 v83, v172 offset:132
	ds_read_b32 v100, v172 offset:8
	ds_read_b32 v84, v172 offset:136
	ds_read_b32 v101, v172 offset:12
	ds_read_b32 v85, v172 offset:140
	ds_read_b32 v102, v172 offset:32
	ds_read_b32 v86, v172 offset:160
	ds_read_b32 v103, v172 offset:36
	ds_read_b32 v87, v172 offset:164
	ds_read_b32 v104, v172 offset:40
	ds_read_b32 v88, v172 offset:168
	ds_read_b32 v105, v172 offset:44
	ds_read_b32 v89, v172 offset:172
	ds_read_b32 v106, v172 offset:64
	ds_read_b32 v90, v172 offset:192
	ds_read_b32 v107, v172 offset:68
	ds_read_b32 v91, v172 offset:196
	ds_read_b32 v108, v172 offset:72
	ds_read_b32 v92, v172 offset:200
	ds_read_b32 v109, v172 offset:76
	ds_read_b32 v93, v172 offset:204
	ds_read_b32 v110, v172 offset:96
	ds_read_b32 v94, v172 offset:224
	ds_read_b32 v111, v172 offset:100
	ds_read_b32 v95, v172 offset:228
	ds_read_b32 v112, v172 offset:104
	ds_read_b32 v96, v172 offset:232
	ds_read_b32 v113, v172 offset:108
	ds_read_b32 v97, v172 offset:236
	s_waitcnt lgkmcnt(0)
	v_add_f32_e32 v66, v66, v98
	v_add_f32_e32 v50, v50, v82
	v_add_f32_e32 v67, v67, v99
	v_add_f32_e32 v51, v51, v83
	v_add_f32_e32 v68, v68, v100
	v_add_f32_e32 v52, v52, v84
	v_add_f32_e32 v69, v69, v101
	v_add_f32_e32 v53, v53, v85
	v_add_f32_e32 v70, v70, v102
	v_add_f32_e32 v54, v54, v86
	v_add_f32_e32 v71, v71, v103
	v_add_f32_e32 v55, v55, v87
	v_add_f32_e32 v72, v72, v104
	v_add_f32_e32 v56, v56, v88
	v_add_f32_e32 v73, v73, v105
	v_add_f32_e32 v57, v57, v89
	v_add_f32_e32 v74, v74, v106
	v_add_f32_e32 v58, v58, v90
	v_add_f32_e32 v75, v75, v107
	v_add_f32_e32 v59, v59, v91
	v_add_f32_e32 v76, v76, v108
	v_add_f32_e32 v60, v60, v92
	v_add_f32_e32 v77, v77, v109
	v_add_f32_e32 v61, v61, v93
	v_add_f32_e32 v78, v78, v110
	v_add_f32_e32 v62, v62, v94
	v_add_f32_e32 v79, v79, v111
	v_add_f32_e32 v63, v63, v95
	v_add_f32_e32 v80, v80, v112
	v_add_f32_e32 v64, v64, v96
	v_add_f32_e32 v81, v81, v113
	v_add_f32_e32 v65, v65, v97
	v_mov_b32_e32 v98, 0xf149f2ca
	v_cndmask_b32_e32 v66, v98, v66, vcc
	v_cndmask_b32_e64 v50, v98, v50, s[8:9]
	v_cndmask_b32_e64 v67, v98, v67, s[42:43]
	v_cndmask_b32_e64 v51, v98, v51, s[10:11]
	v_cndmask_b32_e64 v68, v98, v68, s[44:45]
	v_cndmask_b32_e64 v52, v98, v52, s[12:13]
	v_cndmask_b32_e64 v69, v98, v69, s[46:47]
	v_cndmask_b32_e64 v53, v98, v53, s[14:15]
	v_cndmask_b32_e64 v70, v98, v70, s[48:49]
	v_cndmask_b32_e64 v54, v98, v54, s[16:17]
	v_cndmask_b32_e64 v71, v98, v71, s[50:51]
	v_cndmask_b32_e64 v55, v98, v55, s[18:19]
	v_cndmask_b32_e64 v72, v98, v72, s[52:53]
	v_cndmask_b32_e64 v56, v98, v56, s[24:25]
	v_cndmask_b32_e64 v73, v98, v73, s[54:55]
	v_cndmask_b32_e64 v57, v98, v57, s[86:87]
	v_cndmask_b32_e64 v74, v98, v74, s[30:31]
	v_cndmask_b32_e64 v58, v98, v58, s[56:57]
	v_cndmask_b32_e64 v75, v98, v75, s[34:35]
	v_cndmask_b32_e64 v59, v98, v59, s[58:59]
	v_cndmask_b32_e64 v76, v98, v76, s[96:97]
	v_cndmask_b32_e64 v60, v98, v60, s[60:61]
	v_cndmask_b32_e64 v77, v98, v77, s[76:77]
	v_cndmask_b32_e64 v61, v98, v61, s[62:63]
	v_cndmask_b32_e64 v78, v98, v78, s[28:29]
	v_cndmask_b32_e64 v62, v98, v62, s[64:65]
	v_cndmask_b32_e64 v79, v98, v79, s[94:95]
	v_cndmask_b32_e64 v63, v98, v63, s[66:67]
	v_cndmask_b32_e64 v80, v98, v80, s[92:93]
	v_cndmask_b32_e64 v64, v98, v64, s[68:69]
	v_cndmask_b32_e64 v81, v98, v81, s[88:89]
	v_cndmask_b32_e64 v65, v98, v65, s[70:71]

; template <int KW, int DV, bool NA> ...
;     ...
;         if (NA && i < n1) {
;             const int kr = na_row0 + i, dr = kr - na_r + 7;
;             const int cs = min(max(na_c - 8, 0), 48);
;             const float* rb = rpbs + dr * 31 - na_c + 15;
; #pragma unroll
;             for (int r = 0; r < 16; ++r) {
;                 const int kc0 = (r & 3) + 8 * (r >> 2) + 4 * hi, kc1 = kc0 + 32;
;                 const bool ok0 = (kc0 >= cs) && (kc0 < cs + 16), ok1 = (kc1 >= cs) && (kc1 < cs + 16);
;                 p0[r] = ok0 ? p0[r] + rb[kc0] : -1e30f;
;                 p1[r] = ok1 ? p1[r] + rb[kc1] : -1e30f;
;             }
;         }
.LBB0_509:
	s_or_b64 exec, exec, s[72:73]
	v_cmp_ge_i32_e64 s[82:83], s6, v163
	v_cmp_lt_i32_e64 s[0:1], s6, v163
	s_and_saveexec_b64 s[26:27], s[0:1]
	v_cmp_ge_i32_e64 s[72:73], s6, v164
	v_cmp_lt_i32_e64 s[74:75], s6, v165
	s_and_b64 s[6:7], s[72:73], s[74:75]
	s_andn2_b64 s[36:37], s[82:83], exec
	s_and_b64 s[6:7], s[6:7], exec
	s_or_b64 s[82:83], s[36:37], s[6:7]
	s_or_b64 exec, exec, s[26:27]
	s_mov_b64 s[74:75], s[22:23]
	s_and_saveexec_b64 s[72:73], s[82:83]
	s_cbranch_execz .LBB0_424
	s_movk_i32 s6, 0x5400
	v_mul_lo_u32 v0, v168, s6
	v_add_u32_e32 v0, 0, v0
	v_add3_u32 v86, v0, v166, v167
	ds_read_b128 v[50:53], v86
	ds_read_b128 v[82:85], v86 offset:4608
	s_waitcnt lgkmcnt(1)
	v_mfma_f32_32x32x16_bf16 v[66:81], v[50:53], v[114:117], v[34:49]
	s_waitcnt lgkmcnt(0)
	v_mfma_f32_32x32x16_bf16 v[50:65], v[82:85], v[114:117], v[34:49]
	ds_read_b128 v[82:85], v86 offset:32
	s_waitcnt lgkmcnt(0)
	v_mfma_f32_32x32x16_bf16 v[66:81], v[82:85], v[118:121], v[66:81]
	ds_read_b128 v[82:85], v86 offset:4640
	s_waitcnt lgkmcnt(0)
	v_mfma_f32_32x32x16_bf16 v[50:65], v[82:85], v[118:121], v[50:65]
	ds_read_b128 v[82:85], v86 offset:64
	s_waitcnt lgkmcnt(0)
	v_mfma_f32_32x32x16_bf16 v[66:81], v[82:85], v[122:125], v[66:81]
	ds_read_b128 v[82:85], v86 offset:4672
	s_waitcnt lgkmcnt(0)
	v_mfma_f32_32x32x16_bf16 v[50:65], v[82:85], v[122:125], v[50:65]
	ds_read_b128 v[82:85], v86 offset:96
	s_waitcnt lgkmcnt(0)
	v_mfma_f32_32x32x16_bf16 v[66:81], v[82:85], v[126:129], v[66:81]
	ds_read_b128 v[82:85], v86 offset:4704
	s_waitcnt lgkmcnt(0)
	v_mfma_f32_32x32x16_bf16 v[50:65], v[82:85], v[126:129], v[50:65]
	s_and_saveexec_b64 s[74:75], s[0:1]
	s_cbranch_execz .LBB0_578
	ds_read_b32 v98, v172 offset:124
	ds_read_b32 v82, v172 offset:252
	ds_read_b32 v99, v172 offset:128
	ds_read_b32 v83, v172 offset:256
	ds_read_b32 v100, v172 offset:132
	ds_read_b32 v84, v172 offset:260
	ds_read_b32 v101, v172 offset:136
	ds_read_b32 v85, v172 offset:264
	ds_read_b32 v102, v172 offset:156
	ds_read_b32 v86, v172 offset:284
	ds_read_b32 v103, v172 offset:160
	ds_read_b32 v87, v172 offset:288
	ds_read_b32 v104, v172 offset:164
	ds_read_b32 v88, v172 offset:292
	ds_read_b32 v105, v172 offset:168
	ds_read_b32 v89, v172 offset:296
	ds_read_b32 v106, v172 offset:188
	ds_read_b32 v90, v172 offset:316
	ds_read_b32 v107, v172 offset:192
	ds_read_b32 v91, v172 offset:320
	ds_read_b32 v108, v172 offset:196
	ds_read_b32 v92, v172 offset:324
	ds_read_b32 v109, v172 offset:200
	ds_read_b32 v93, v172 offset:328
	ds_read_b32 v110, v172 offset:220
	ds_read_b32 v94, v172 offset:348
	ds_read_b32 v111, v172 offset:224
	ds_read_b32 v95, v172 offset:352
	ds_read_b32 v112, v172 offset:228
	ds_read_b32 v96, v172 offset:356
	ds_read_b32 v113, v172 offset:232
	ds_read_b32 v97, v172 offset:360
	s_waitcnt lgkmcnt(0)
	v_add_f32_e32 v66, v66, v98
	v_add_f32_e32 v50, v50, v82
	v_add_f32_e32 v67, v67, v99
	v_add_f32_e32 v51, v51, v83
	v_add_f32_e32 v68, v68, v100
	v_add_f32_e32 v52, v52, v84
	v_add_f32_e32 v69, v69, v101
	v_add_f32_e32 v53, v53, v85
	v_add_f32_e32 v70, v70, v102
	v_add_f32_e32 v54, v54, v86
	v_add_f32_e32 v71, v71, v103
	v_add_f32_e32 v55, v55, v87
	v_add_f32_e32 v72, v72, v104
	v_add_f32_e32 v56, v56, v88
	v_add_f32_e32 v73, v73, v105
	v_add_f32_e32 v57, v57, v89
	v_add_f32_e32 v74, v74, v106
	v_add_f32_e32 v58, v58, v90
	v_add_f32_e32 v75, v75, v107
	v_add_f32_e32 v59, v59, v91
	v_add_f32_e32 v76, v76, v108
	v_add_f32_e32 v60, v60, v92
	v_add_f32_e32 v77, v77, v109
	v_add_f32_e32 v61, v61, v93
	v_add_f32_e32 v78, v78, v110
	v_add_f32_e32 v62, v62, v94
	v_add_f32_e32 v79, v79, v111
	v_add_f32_e32 v63, v63, v95
	v_add_f32_e32 v80, v80, v112
	v_add_f32_e32 v64, v64, v96
	v_add_f32_e32 v81, v81, v113
	v_add_f32_e32 v65, v65, v97
	v_mov_b32_e32 v98, 0xf149f2ca
	v_cndmask_b32_e32 v66, v98, v66, vcc
	v_cndmask_b32_e64 v50, v98, v50, s[8:9]
	v_cndmask_b32_e64 v67, v98, v67, s[42:43]
	v_cndmask_b32_e64 v51, v98, v51, s[10:11]
	v_cndmask_b32_e64 v68, v98, v68, s[44:45]
	v_cndmask_b32_e64 v52, v98, v52, s[12:13]
	v_cndmask_b32_e64 v69, v98, v69, s[46:47]
	v_cndmask_b32_e64 v53, v98, v53, s[14:15]
	v_cndmask_b32_e64 v70, v98, v70, s[48:49]
	v_cndmask_b32_e64 v54, v98, v54, s[16:17]
	v_cndmask_b32_e64 v71, v98, v71, s[50:51]
	v_cndmask_b32_e64 v55, v98, v55, s[18:19]
	v_cndmask_b32_e64 v72, v98, v72, s[52:53]
	v_cndmask_b32_e64 v56, v98, v56, s[24:25]
	v_cndmask_b32_e64 v73, v98, v73, s[54:55]
	v_cndmask_b32_e64 v57, v98, v57, s[86:87]
	v_cndmask_b32_e64 v74, v98, v74, s[30:31]
	v_cndmask_b32_e64 v58, v98, v58, s[56:57]
	v_cndmask_b32_e64 v75, v98, v75, s[34:35]
	v_cndmask_b32_e64 v59, v98, v59, s[58:59]
	v_cndmask_b32_e64 v76, v98, v76, s[96:97]
	v_cndmask_b32_e64 v60, v98, v60, s[60:61]
	v_cndmask_b32_e64 v77, v98, v77, s[76:77]
	v_cndmask_b32_e64 v61, v98, v61, s[62:63]
	v_cndmask_b32_e64 v78, v98, v78, s[28:29]
	v_cndmask_b32_e64 v62, v98, v62, s[64:65]
	v_cndmask_b32_e64 v79, v98, v79, s[94:95]
	v_cndmask_b32_e64 v63, v98, v63, s[66:67]
	v_cndmask_b32_e64 v80, v98, v80, s[92:93]
	v_cndmask_b32_e64 v64, v98, v64, s[68:69]
	v_cndmask_b32_e64 v81, v98, v81, s[88:89]
	v_cndmask_b32_e64 v65, v98, v65, s[70:71]
